# K-loop compute-segment heads: priority raised before parking at the barrier (SP1 blocks), redundant lgkmcnt(0) behind it dropped, narrow-flag v_cmp moved out of the post-barrier path
# speedup vs baseline: 1.0113x; 1.0113x over previous
.LBB0_318:
	v_add_u32_e32 v128, 0x10000, v251
	ds_read_b128 v[146:149], v128
	ds_read_b128 v[150:153], v128 offset:1024
	ds_read_b128 v[154:157], v128 offset:2048
	ds_read_b128 v[158:161], v128 offset:3072
	v_add_u32_e32 v128, 0x14000, v251
	ds_read_b128 v[130:133], v128
	ds_read_b128 v[134:137], v128 offset:1024
	ds_read_b128 v[138:141], v128 offset:2048
	ds_read_b128 v[142:145], v128 offset:3072
	s_add_u32 s42, s93, s9
	s_addc_u32 s43, s94, 0
	s_add_u32 s42, s42, 0xffffff80
	s_addc_u32 s43, s43, -1
	s_mov_b32 s74, m0
	s_mov_b32 m0, s65
	s_nop 0
	global_load_lds_dwordx4 v245, s[42:43]
	s_mov_b32 m0, s74
	s_nop 0
	s_mov_b32 s74, m0
	s_mov_b32 m0, s66
	s_nop 0
	global_load_lds_dwordx4 v247, s[42:43]
	s_mov_b32 m0, s74
	s_cmp_eq_u32 s57, s3
	s_cselect_b32 s73, s55, s94
	s_cselect_b32 s72, s54, s93
	s_cselect_b32 s77, s63, s92
	s_cselect_b32 s76, s62, s8
	s_waitcnt lgkmcnt(0)
	ds_read_b128 v[162:165], v252
	ds_read_b128 v[166:169], v252 offset:1024
	ds_read_b128 v[170:173], v252 offset:2048
	ds_read_b128 v[174:177], v252 offset:3072
	ds_read_b128 v[178:181], v252 offset:4096
	ds_read_b128 v[182:185], v252 offset:5120
	ds_read_b128 v[186:189], v252 offset:6144
	ds_read_b128 v[190:193], v252 offset:7168
	s_waitcnt vmcnt(8)
	s_waitcnt lgkmcnt(0)
	s_setprio 1
	s_barrier
	v_mfma_f32_16x16x32_bf16 v[124:127], v[146:149], v[162:165], v[124:127]
	v_mfma_f32_16x16x32_bf16 v[120:123], v[154:157], v[162:165], v[120:123]
	v_mfma_f32_16x16x32_bf16 v[108:111], v[146:149], v[170:173], v[108:111]
	v_mfma_f32_16x16x32_bf16 v[104:107], v[154:157], v[170:173], v[104:107]
	v_mfma_f32_16x16x32_bf16 v[92:95], v[146:149], v[178:181], v[92:95]
	v_mfma_f32_16x16x32_bf16 v[88:91], v[154:157], v[178:181], v[88:91]
	v_mfma_f32_16x16x32_bf16 v[76:79], v[146:149], v[186:189], v[76:79]
	v_mfma_f32_16x16x32_bf16 v[72:75], v[154:157], v[186:189], v[72:75]
	v_mfma_f32_16x16x32_bf16 v[124:127], v[150:153], v[166:169], v[124:127]
	v_mfma_f32_16x16x32_bf16 v[120:123], v[158:161], v[166:169], v[120:123]
	v_mfma_f32_16x16x32_bf16 v[108:111], v[150:153], v[174:177], v[108:111]
	v_mfma_f32_16x16x32_bf16 v[104:107], v[158:161], v[174:177], v[104:107]
	v_mfma_f32_16x16x32_bf16 v[92:95], v[150:153], v[182:185], v[92:95]
	v_mfma_f32_16x16x32_bf16 v[88:91], v[158:161], v[182:185], v[88:91]
	v_mfma_f32_16x16x32_bf16 v[76:79], v[150:153], v[190:193], v[76:79]
	v_mfma_f32_16x16x32_bf16 v[72:75], v[158:161], v[190:193], v[72:75]
	s_setprio 0
	s_setprio 1
	v_mfma_f32_16x16x32_bf16 v[116:119], v[130:133], v[162:165], v[116:119]
	v_mfma_f32_16x16x32_bf16 v[112:115], v[138:141], v[162:165], v[112:115]
	v_mfma_f32_16x16x32_bf16 v[100:103], v[130:133], v[170:173], v[100:103]
	v_mfma_f32_16x16x32_bf16 v[96:99], v[138:141], v[170:173], v[96:99]
	v_mfma_f32_16x16x32_bf16 v[84:87], v[130:133], v[178:181], v[84:87]
	v_mfma_f32_16x16x32_bf16 v[80:83], v[138:141], v[178:181], v[80:83]
	v_mfma_f32_16x16x32_bf16 v[68:71], v[130:133], v[186:189], v[68:71]
	v_mfma_f32_16x16x32_bf16 v[64:67], v[138:141], v[186:189], v[64:67]
	v_mfma_f32_16x16x32_bf16 v[116:119], v[134:137], v[166:169], v[116:119]
	v_mfma_f32_16x16x32_bf16 v[112:115], v[142:145], v[166:169], v[112:115]
	v_mfma_f32_16x16x32_bf16 v[100:103], v[134:137], v[174:177], v[100:103]
	v_mfma_f32_16x16x32_bf16 v[96:99], v[142:145], v[174:177], v[96:99]
	v_mfma_f32_16x16x32_bf16 v[84:87], v[134:137], v[182:185], v[84:87]
	v_mfma_f32_16x16x32_bf16 v[80:83], v[142:145], v[182:185], v[80:83]
	v_mfma_f32_16x16x32_bf16 v[68:71], v[134:137], v[190:193], v[68:71]
	v_mfma_f32_16x16x32_bf16 v[64:67], v[142:145], v[190:193], v[64:67]
	s_setprio 0
	s_barrier
	s_mov_b32 s42, m0
	s_mov_b32 m0, s14
	s_nop 0
	global_load_lds_dwordx4 v246, s[76:77]
	s_mov_b32 m0, s42
	s_add_u32 s74, s76, s9
	s_mov_b32 s42, m0
	s_mov_b32 m0, s15
	s_nop 0
	global_load_lds_dwordx4 v248, s[76:77]
	s_mov_b32 m0, s42
	s_addc_u32 s75, s77, 0
	s_mov_b32 s42, m0
	s_mov_b32 m0, s16
	s_nop 0
	global_load_lds_dwordx4 v246, s[74:75]
	s_mov_b32 m0, s42
	v_cndmask_b32_e64 v128, 0, 1, s[68:69]
	s_mov_b32 s42, m0
	s_mov_b32 m0, s17
	s_nop 0
	global_load_lds_dwordx4 v248, s[74:75]
	s_mov_b32 m0, s42
	s_andn2_b64 vcc, exec, s[68:69]
	s_mov_b32 s42, m0
	s_mov_b32 m0, s11
	s_nop 0
	global_load_lds_dwordx4 v245, s[72:73]
	s_mov_b32 m0, s42
	s_nop 0
	s_mov_b32 s42, m0
	s_mov_b32 m0, s19
	s_nop 0
	global_load_lds_dwordx4 v247, s[72:73]
	s_mov_b32 m0, s42
	ds_read_b128 v[186:189], v252 offset:16384
	ds_read_b128 v[190:193], v252 offset:17408
	ds_read_b128 v[178:181], v252 offset:18432
	ds_read_b128 v[182:185], v252 offset:19456
	ds_read_b128 v[170:173], v252 offset:20480
	ds_read_b128 v[174:177], v252 offset:21504
	ds_read_b128 v[162:165], v252 offset:22528
	ds_read_b128 v[166:169], v252 offset:23552
	v_cmp_ne_u32_e64 s[42:43], 1, v128
	s_waitcnt vmcnt(8)
	s_waitcnt lgkmcnt(0)
	s_barrier
	s_cbranch_vccnz .LBB0_320
	s_setprio 1
	v_mfma_f32_16x16x32_bf16 v[60:63], v[146:149], v[186:189], v[60:63]
	v_mfma_f32_16x16x32_bf16 v[56:59], v[154:157], v[186:189], v[56:59]
	v_mfma_f32_16x16x32_bf16 v[44:47], v[146:149], v[178:181], v[44:47]
	v_mfma_f32_16x16x32_bf16 v[40:43], v[154:157], v[178:181], v[40:43]
	v_mfma_f32_16x16x32_bf16 v[28:31], v[146:149], v[170:173], v[28:31]
	v_mfma_f32_16x16x32_bf16 v[24:27], v[154:157], v[170:173], v[24:27]
	v_mfma_f32_16x16x32_bf16 v[12:15], v[146:149], v[162:165], v[12:15]
	v_mfma_f32_16x16x32_bf16 v[8:11], v[154:157], v[162:165], v[8:11]
	v_mfma_f32_16x16x32_bf16 v[60:63], v[150:153], v[190:193], v[60:63]
	v_mfma_f32_16x16x32_bf16 v[56:59], v[158:161], v[190:193], v[56:59]
	v_mfma_f32_16x16x32_bf16 v[44:47], v[150:153], v[182:185], v[44:47]
	v_mfma_f32_16x16x32_bf16 v[40:43], v[158:161], v[182:185], v[40:43]
	v_mfma_f32_16x16x32_bf16 v[28:31], v[150:153], v[174:177], v[28:31]
	v_mfma_f32_16x16x32_bf16 v[24:27], v[158:161], v[174:177], v[24:27]
	v_mfma_f32_16x16x32_bf16 v[12:15], v[150:153], v[166:169], v[12:15]
	v_mfma_f32_16x16x32_bf16 v[8:11], v[158:161], v[166:169], v[8:11]
	s_setprio 0
	s_setprio 1
	v_mfma_f32_16x16x32_bf16 v[52:55], v[130:133], v[186:189], v[52:55]
	v_mfma_f32_16x16x32_bf16 v[48:51], v[138:141], v[186:189], v[48:51]
	v_mfma_f32_16x16x32_bf16 v[36:39], v[130:133], v[178:181], v[36:39]
	v_mfma_f32_16x16x32_bf16 v[32:35], v[138:141], v[178:181], v[32:35]
	v_mfma_f32_16x16x32_bf16 v[20:23], v[130:133], v[170:173], v[20:23]
	v_mfma_f32_16x16x32_bf16 v[16:19], v[138:141], v[170:173], v[16:19]
	v_mfma_f32_16x16x32_bf16 v[4:7], v[130:133], v[162:165], v[4:7]
	v_mfma_f32_16x16x32_bf16 v[0:3], v[138:141], v[162:165], v[0:3]
	v_mfma_f32_16x16x32_bf16 v[52:55], v[134:137], v[190:193], v[52:55]
	v_mfma_f32_16x16x32_bf16 v[48:51], v[142:145], v[190:193], v[48:51]
	v_mfma_f32_16x16x32_bf16 v[36:39], v[134:137], v[182:185], v[36:39]
	v_mfma_f32_16x16x32_bf16 v[32:35], v[142:145], v[182:185], v[32:35]
	v_mfma_f32_16x16x32_bf16 v[20:23], v[134:137], v[174:177], v[20:23]
	v_mfma_f32_16x16x32_bf16 v[16:19], v[142:145], v[174:177], v[16:19]
	v_mfma_f32_16x16x32_bf16 v[4:7], v[134:137], v[166:169], v[4:7]
	v_mfma_f32_16x16x32_bf16 v[0:3], v[142:145], v[166:169], v[0:3]
	s_setprio 0
.LBB0_320:
	s_add_u32 s80, s72, 0x80
	s_addc_u32 s81, s73, 0
	s_add_u32 s76, s76, 0x80
	s_addc_u32 s77, s77, 0
	s_barrier
	v_add_u32_e32 v128, 0x18000, v251
	ds_read_b128 v[146:149], v128
	ds_read_b128 v[150:153], v128 offset:1024
	ds_read_b128 v[154:157], v128 offset:2048
	ds_read_b128 v[158:161], v128 offset:3072
	v_add_u32_e32 v128, 0x1c000, v251
	ds_read_b128 v[130:133], v128
	ds_read_b128 v[134:137], v128 offset:1024
	ds_read_b128 v[138:141], v128 offset:2048
	ds_read_b128 v[142:145], v128 offset:3072
	s_add_u32 s72, s72, s9
	s_addc_u32 s73, s73, 0
	s_mov_b32 s95, m0
	s_mov_b32 m0, s20
	s_nop 0
	global_load_lds_dwordx4 v245, s[72:73]
	s_mov_b32 m0, s95
	s_nop 0
	s_mov_b32 s95, m0
	s_mov_b32 m0, s21
	s_nop 0
	global_load_lds_dwordx4 v247, s[72:73]
	s_mov_b32 m0, s95
	s_waitcnt lgkmcnt(0)
	ds_read_b128 v[162:165], v252 offset:32768
	ds_read_b128 v[166:169], v252 offset:33792
	ds_read_b128 v[170:173], v252 offset:34816
	ds_read_b128 v[174:177], v252 offset:35840
	ds_read_b128 v[178:181], v252 offset:36864
	ds_read_b128 v[182:185], v252 offset:37888
	ds_read_b128 v[186:189], v252 offset:38912
	ds_read_b128 v[190:193], v252 offset:39936
	s_waitcnt vmcnt(8)
	s_waitcnt lgkmcnt(0)
	s_setprio 1
	s_barrier
	v_mfma_f32_16x16x32_bf16 v[124:127], v[146:149], v[162:165], v[124:127]
	v_mfma_f32_16x16x32_bf16 v[120:123], v[154:157], v[162:165], v[120:123]
	v_mfma_f32_16x16x32_bf16 v[108:111], v[146:149], v[170:173], v[108:111]
	v_mfma_f32_16x16x32_bf16 v[104:107], v[154:157], v[170:173], v[104:107]
	v_mfma_f32_16x16x32_bf16 v[92:95], v[146:149], v[178:181], v[92:95]
	v_mfma_f32_16x16x32_bf16 v[88:91], v[154:157], v[178:181], v[88:91]
	v_mfma_f32_16x16x32_bf16 v[76:79], v[146:149], v[186:189], v[76:79]
	v_mfma_f32_16x16x32_bf16 v[72:75], v[154:157], v[186:189], v[72:75]
	v_mfma_f32_16x16x32_bf16 v[124:127], v[150:153], v[166:169], v[124:127]
	v_mfma_f32_16x16x32_bf16 v[120:123], v[158:161], v[166:169], v[120:123]
	v_mfma_f32_16x16x32_bf16 v[108:111], v[150:153], v[174:177], v[108:111]
	v_mfma_f32_16x16x32_bf16 v[104:107], v[158:161], v[174:177], v[104:107]
	v_mfma_f32_16x16x32_bf16 v[92:95], v[150:153], v[182:185], v[92:95]
	v_mfma_f32_16x16x32_bf16 v[88:91], v[158:161], v[182:185], v[88:91]
	v_mfma_f32_16x16x32_bf16 v[76:79], v[150:153], v[190:193], v[76:79]
	v_mfma_f32_16x16x32_bf16 v[72:75], v[158:161], v[190:193], v[72:75]
	s_setprio 0
	s_setprio 1
	v_mfma_f32_16x16x32_bf16 v[116:119], v[130:133], v[162:165], v[116:119]
	v_mfma_f32_16x16x32_bf16 v[112:115], v[138:141], v[162:165], v[112:115]
	v_mfma_f32_16x16x32_bf16 v[100:103], v[130:133], v[170:173], v[100:103]
	v_mfma_f32_16x16x32_bf16 v[96:99], v[138:141], v[170:173], v[96:99]
	v_mfma_f32_16x16x32_bf16 v[84:87], v[130:133], v[178:181], v[84:87]
	v_mfma_f32_16x16x32_bf16 v[80:83], v[138:141], v[178:181], v[80:83]
	v_mfma_f32_16x16x32_bf16 v[68:71], v[130:133], v[186:189], v[68:71]
	v_mfma_f32_16x16x32_bf16 v[64:67], v[138:141], v[186:189], v[64:67]
	v_mfma_f32_16x16x32_bf16 v[116:119], v[134:137], v[166:169], v[116:119]
	v_mfma_f32_16x16x32_bf16 v[112:115], v[142:145], v[166:169], v[112:115]
	v_mfma_f32_16x16x32_bf16 v[100:103], v[134:137], v[174:177], v[100:103]
	v_mfma_f32_16x16x32_bf16 v[96:99], v[142:145], v[174:177], v[96:99]
	v_mfma_f32_16x16x32_bf16 v[84:87], v[134:137], v[182:185], v[84:87]
	v_mfma_f32_16x16x32_bf16 v[80:83], v[142:145], v[182:185], v[80:83]
	v_mfma_f32_16x16x32_bf16 v[68:71], v[134:137], v[190:193], v[68:71]
	v_mfma_f32_16x16x32_bf16 v[64:67], v[142:145], v[190:193], v[64:67]
	s_setprio 0
	s_barrier
	s_mov_b32 s72, m0
	s_mov_b32 m0, s23
	s_nop 0
	global_load_lds_dwordx4 v246, s[76:77]
	s_mov_b32 m0, s72
	s_nop 0
	s_mov_b32 s72, m0
	s_mov_b32 m0, s30
	s_nop 0
	global_load_lds_dwordx4 v248, s[76:77]
	s_mov_b32 m0, s72
	s_add_u32 s72, s74, 0x80
	s_addc_u32 s73, s75, 0
	s_mov_b32 s74, m0
	s_mov_b32 m0, s52
	s_nop 0
	global_load_lds_dwordx4 v246, s[72:73]
	s_mov_b32 m0, s74
	s_and_b64 vcc, exec, s[42:43]
	s_mov_b32 s74, m0
	s_mov_b32 m0, s53
	s_nop 0
	global_load_lds_dwordx4 v248, s[72:73]
	s_mov_b32 m0, s74
	s_mov_b32 s72, m0
	s_mov_b32 m0, s47
	s_nop 0
	global_load_lds_dwordx4 v245, s[80:81]
	s_mov_b32 m0, s72
	s_nop 0
	s_mov_b32 s72, m0
	s_mov_b32 m0, s50
	s_nop 0
	global_load_lds_dwordx4 v247, s[80:81]
	s_mov_b32 m0, s72
	ds_read_b128 v[186:189], v252 offset:49152
	ds_read_b128 v[190:193], v252 offset:50176
	ds_read_b128 v[178:181], v252 offset:51200
	ds_read_b128 v[182:185], v252 offset:52224
	ds_read_b128 v[170:173], v252 offset:53248
	ds_read_b128 v[174:177], v252 offset:54272
	ds_read_b128 v[162:165], v252 offset:55296
	ds_read_b128 v[166:169], v252 offset:56320
	s_waitcnt vmcnt(8)
	s_waitcnt lgkmcnt(0)
	s_barrier
	s_cbranch_vccnz .LBB0_317
	s_setprio 1
	v_mfma_f32_16x16x32_bf16 v[60:63], v[146:149], v[186:189], v[60:63]
	v_mfma_f32_16x16x32_bf16 v[56:59], v[154:157], v[186:189], v[56:59]
	v_mfma_f32_16x16x32_bf16 v[44:47], v[146:149], v[178:181], v[44:47]
	v_mfma_f32_16x16x32_bf16 v[40:43], v[154:157], v[178:181], v[40:43]
	v_mfma_f32_16x16x32_bf16 v[28:31], v[146:149], v[170:173], v[28:31]
	v_mfma_f32_16x16x32_bf16 v[24:27], v[154:157], v[170:173], v[24:27]
	v_mfma_f32_16x16x32_bf16 v[12:15], v[146:149], v[162:165], v[12:15]
	v_mfma_f32_16x16x32_bf16 v[8:11], v[154:157], v[162:165], v[8:11]
	v_mfma_f32_16x16x32_bf16 v[60:63], v[150:153], v[190:193], v[60:63]
	v_mfma_f32_16x16x32_bf16 v[56:59], v[158:161], v[190:193], v[56:59]
	v_mfma_f32_16x16x32_bf16 v[44:47], v[150:153], v[182:185], v[44:47]
	v_mfma_f32_16x16x32_bf16 v[40:43], v[158:161], v[182:185], v[40:43]
	v_mfma_f32_16x16x32_bf16 v[28:31], v[150:153], v[174:177], v[28:31]
	v_mfma_f32_16x16x32_bf16 v[24:27], v[158:161], v[174:177], v[24:27]
	v_mfma_f32_16x16x32_bf16 v[12:15], v[150:153], v[166:169], v[12:15]
	v_mfma_f32_16x16x32_bf16 v[8:11], v[158:161], v[166:169], v[8:11]
	s_setprio 0
	s_setprio 1
	v_mfma_f32_16x16x32_bf16 v[52:55], v[130:133], v[186:189], v[52:55]
	v_mfma_f32_16x16x32_bf16 v[48:51], v[138:141], v[186:189], v[48:51]
	v_mfma_f32_16x16x32_bf16 v[36:39], v[130:133], v[178:181], v[36:39]
	v_mfma_f32_16x16x32_bf16 v[32:35], v[138:141], v[178:181], v[32:35]
	v_mfma_f32_16x16x32_bf16 v[20:23], v[130:133], v[170:173], v[20:23]
	v_mfma_f32_16x16x32_bf16 v[16:19], v[138:141], v[170:173], v[16:19]
	v_mfma_f32_16x16x32_bf16 v[4:7], v[130:133], v[162:165], v[4:7]
	v_mfma_f32_16x16x32_bf16 v[0:3], v[138:141], v[162:165], v[0:3]
	v_mfma_f32_16x16x32_bf16 v[52:55], v[134:137], v[190:193], v[52:55]
	v_mfma_f32_16x16x32_bf16 v[48:51], v[142:145], v[190:193], v[48:51]
	v_mfma_f32_16x16x32_bf16 v[36:39], v[134:137], v[182:185], v[36:39]
	v_mfma_f32_16x16x32_bf16 v[32:35], v[142:145], v[182:185], v[32:35]
	v_mfma_f32_16x16x32_bf16 v[20:23], v[134:137], v[174:177], v[20:23]
	v_mfma_f32_16x16x32_bf16 v[16:19], v[142:145], v[174:177], v[16:19]
	v_mfma_f32_16x16x32_bf16 v[4:7], v[134:137], v[166:169], v[4:7]
	v_mfma_f32_16x16x32_bf16 v[0:3], v[142:145], v[166:169], v[0:3]
	s_setprio 0
	s_branch .LBB0_317

.LBB0_413:
	v_add_u32_e32 v128, 0x10000, v208
	ds_read_b128 v[146:149], v128
	ds_read_b128 v[150:153], v128 offset:1024
	ds_read_b128 v[154:157], v128 offset:2048
	ds_read_b128 v[158:161], v128 offset:3072
	v_add_u32_e32 v128, 0x14000, v208
	ds_read_b128 v[130:133], v128
	ds_read_b128 v[134:137], v128 offset:1024
	ds_read_b128 v[138:141], v128 offset:2048
	ds_read_b128 v[142:145], v128 offset:3072
	s_mov_b32 s38, m0
	s_mov_b32 m0, s30
	s_nop 0
	global_load_lds_dwordx4 v195, s[46:47]
	s_mov_b32 m0, s38
	s_nop 0
	s_mov_b32 s38, m0
	s_mov_b32 m0, s14
	s_nop 0
	global_load_lds_dwordx4 v197, s[46:47]
	s_mov_b32 m0, s38
	s_add_u32 s38, s46, 0xfffc0080
	s_addc_u32 s39, s47, -1
	s_cmp_eq_u32 s19, 12
	s_cselect_b32 s75, s27, s39
	s_cselect_b32 s74, s99, s38
	s_cselect_b32 s63, s23, s18
	s_cselect_b32 s62, s3, s8
	s_waitcnt lgkmcnt(0)
	ds_read_b128 v[162:165], v209
	ds_read_b128 v[166:169], v209 offset:1024
	ds_read_b128 v[170:173], v209 offset:2048
	ds_read_b128 v[174:177], v209 offset:3072
	ds_read_b128 v[178:181], v209 offset:4096
	ds_read_b128 v[182:185], v209 offset:5120
	ds_read_b128 v[186:189], v209 offset:6144
	ds_read_b128 v[190:193], v209 offset:7168
	s_waitcnt vmcnt(8)
	s_waitcnt lgkmcnt(0)
	s_setprio 1
	s_barrier
	v_mfma_f32_16x16x32_bf16 v[124:127], v[146:149], v[162:165], v[124:127]
	v_mfma_f32_16x16x32_bf16 v[120:123], v[154:157], v[162:165], v[120:123]
	v_mfma_f32_16x16x32_bf16 v[108:111], v[146:149], v[170:173], v[108:111]
	v_mfma_f32_16x16x32_bf16 v[104:107], v[154:157], v[170:173], v[104:107]
	v_mfma_f32_16x16x32_bf16 v[92:95], v[146:149], v[178:181], v[92:95]
	v_mfma_f32_16x16x32_bf16 v[88:91], v[154:157], v[178:181], v[88:91]
	v_mfma_f32_16x16x32_bf16 v[76:79], v[146:149], v[186:189], v[76:79]
	v_mfma_f32_16x16x32_bf16 v[72:75], v[154:157], v[186:189], v[72:75]
	v_mfma_f32_16x16x32_bf16 v[124:127], v[150:153], v[166:169], v[124:127]
	v_mfma_f32_16x16x32_bf16 v[120:123], v[158:161], v[166:169], v[120:123]
	v_mfma_f32_16x16x32_bf16 v[108:111], v[150:153], v[174:177], v[108:111]
	v_mfma_f32_16x16x32_bf16 v[104:107], v[158:161], v[174:177], v[104:107]
	v_mfma_f32_16x16x32_bf16 v[92:95], v[150:153], v[182:185], v[92:95]
	v_mfma_f32_16x16x32_bf16 v[88:91], v[158:161], v[182:185], v[88:91]
	v_mfma_f32_16x16x32_bf16 v[76:79], v[150:153], v[190:193], v[76:79]
	v_mfma_f32_16x16x32_bf16 v[72:75], v[158:161], v[190:193], v[72:75]
	s_setprio 0
	s_setprio 1
	v_mfma_f32_16x16x32_bf16 v[116:119], v[130:133], v[162:165], v[116:119]
	v_mfma_f32_16x16x32_bf16 v[112:115], v[138:141], v[162:165], v[112:115]
	v_mfma_f32_16x16x32_bf16 v[100:103], v[130:133], v[170:173], v[100:103]
	v_mfma_f32_16x16x32_bf16 v[96:99], v[138:141], v[170:173], v[96:99]
	v_mfma_f32_16x16x32_bf16 v[84:87], v[130:133], v[178:181], v[84:87]
	v_mfma_f32_16x16x32_bf16 v[80:83], v[138:141], v[178:181], v[80:83]
	v_mfma_f32_16x16x32_bf16 v[68:71], v[130:133], v[186:189], v[68:71]
	v_mfma_f32_16x16x32_bf16 v[64:67], v[138:141], v[186:189], v[64:67]
	v_mfma_f32_16x16x32_bf16 v[116:119], v[134:137], v[166:169], v[116:119]
	v_mfma_f32_16x16x32_bf16 v[112:115], v[142:145], v[166:169], v[112:115]
	v_mfma_f32_16x16x32_bf16 v[100:103], v[134:137], v[174:177], v[100:103]
	v_mfma_f32_16x16x32_bf16 v[96:99], v[142:145], v[174:177], v[96:99]
	v_mfma_f32_16x16x32_bf16 v[84:87], v[134:137], v[182:185], v[84:87]
	v_mfma_f32_16x16x32_bf16 v[80:83], v[142:145], v[182:185], v[80:83]
	v_mfma_f32_16x16x32_bf16 v[68:71], v[134:137], v[190:193], v[68:71]
	v_mfma_f32_16x16x32_bf16 v[64:67], v[142:145], v[190:193], v[64:67]
	s_setprio 0
	s_barrier
	s_mov_b32 s38, m0
	s_mov_b32 m0, s67
	s_nop 0
	global_load_lds_dwordx4 v196, s[62:63]
	s_mov_b32 m0, s38
	s_add_u32 s44, s62, 0x40000
	s_mov_b32 s38, m0
	s_mov_b32 m0, s86
	s_nop 0
	global_load_lds_dwordx4 v198, s[62:63]
	s_mov_b32 m0, s38
	s_addc_u32 s45, s63, 0
	s_mov_b32 s38, m0
	s_mov_b32 m0, s87
	s_nop 0
	global_load_lds_dwordx4 v196, s[44:45]
	s_mov_b32 m0, s38
	v_cndmask_b32_e64 v128, 0, 1, s[72:73]
	s_mov_b32 s38, m0
	s_mov_b32 m0, s88
	s_nop 0
	global_load_lds_dwordx4 v198, s[44:45]
	s_mov_b32 m0, s38
	v_cmp_ne_u32_e64 s[44:45], 1, v128
	s_mov_b32 s38, m0
	s_mov_b32 m0, s51
	s_nop 0
	global_load_lds_dwordx4 v195, s[74:75]
	s_mov_b32 m0, s38
	s_andn2_b64 vcc, exec, s[72:73]
	s_mov_b32 s38, m0
	s_mov_b32 m0, s89
	s_nop 0
	global_load_lds_dwordx4 v197, s[74:75]
	s_mov_b32 m0, s38
	ds_read_b128 v[186:189], v209 offset:16384
	ds_read_b128 v[190:193], v209 offset:17408
	ds_read_b128 v[178:181], v209 offset:18432
	ds_read_b128 v[182:185], v209 offset:19456
	ds_read_b128 v[170:173], v209 offset:20480
	ds_read_b128 v[174:177], v209 offset:21504
	ds_read_b128 v[162:165], v209 offset:22528
	ds_read_b128 v[166:169], v209 offset:23552
	s_waitcnt vmcnt(8)
	s_waitcnt lgkmcnt(0)
	s_barrier
	s_cbranch_vccnz .LBB0_415
	s_setprio 1
	v_mfma_f32_16x16x32_bf16 v[60:63], v[146:149], v[186:189], v[60:63]
	v_mfma_f32_16x16x32_bf16 v[56:59], v[154:157], v[186:189], v[56:59]
	v_mfma_f32_16x16x32_bf16 v[44:47], v[146:149], v[178:181], v[44:47]
	v_mfma_f32_16x16x32_bf16 v[40:43], v[154:157], v[178:181], v[40:43]
	v_mfma_f32_16x16x32_bf16 v[28:31], v[146:149], v[170:173], v[28:31]
	v_mfma_f32_16x16x32_bf16 v[24:27], v[154:157], v[170:173], v[24:27]
	v_mfma_f32_16x16x32_bf16 v[12:15], v[146:149], v[162:165], v[12:15]
	v_mfma_f32_16x16x32_bf16 v[8:11], v[154:157], v[162:165], v[8:11]
	v_mfma_f32_16x16x32_bf16 v[60:63], v[150:153], v[190:193], v[60:63]
	v_mfma_f32_16x16x32_bf16 v[56:59], v[158:161], v[190:193], v[56:59]
	v_mfma_f32_16x16x32_bf16 v[44:47], v[150:153], v[182:185], v[44:47]
	v_mfma_f32_16x16x32_bf16 v[40:43], v[158:161], v[182:185], v[40:43]
	v_mfma_f32_16x16x32_bf16 v[28:31], v[150:153], v[174:177], v[28:31]
	v_mfma_f32_16x16x32_bf16 v[24:27], v[158:161], v[174:177], v[24:27]
	v_mfma_f32_16x16x32_bf16 v[12:15], v[150:153], v[166:169], v[12:15]
	v_mfma_f32_16x16x32_bf16 v[8:11], v[158:161], v[166:169], v[8:11]
	s_setprio 0
	s_setprio 1
	v_mfma_f32_16x16x32_bf16 v[52:55], v[130:133], v[186:189], v[52:55]
	v_mfma_f32_16x16x32_bf16 v[48:51], v[138:141], v[186:189], v[48:51]
	v_mfma_f32_16x16x32_bf16 v[36:39], v[130:133], v[178:181], v[36:39]
	v_mfma_f32_16x16x32_bf16 v[32:35], v[138:141], v[178:181], v[32:35]
	v_mfma_f32_16x16x32_bf16 v[20:23], v[130:133], v[170:173], v[20:23]
	v_mfma_f32_16x16x32_bf16 v[16:19], v[138:141], v[170:173], v[16:19]
	v_mfma_f32_16x16x32_bf16 v[4:7], v[130:133], v[162:165], v[4:7]
	v_mfma_f32_16x16x32_bf16 v[0:3], v[138:141], v[162:165], v[0:3]
	v_mfma_f32_16x16x32_bf16 v[52:55], v[134:137], v[190:193], v[52:55]
	v_mfma_f32_16x16x32_bf16 v[48:51], v[142:145], v[190:193], v[48:51]
	v_mfma_f32_16x16x32_bf16 v[36:39], v[134:137], v[182:185], v[36:39]
	v_mfma_f32_16x16x32_bf16 v[32:35], v[142:145], v[182:185], v[32:35]
	v_mfma_f32_16x16x32_bf16 v[20:23], v[134:137], v[174:177], v[20:23]
	v_mfma_f32_16x16x32_bf16 v[16:19], v[142:145], v[174:177], v[16:19]
	v_mfma_f32_16x16x32_bf16 v[4:7], v[134:137], v[166:169], v[4:7]
	v_mfma_f32_16x16x32_bf16 v[0:3], v[142:145], v[166:169], v[0:3]
	s_setprio 0
.LBB0_415:
	s_add_u32 s76, s74, 0x80
	s_addc_u32 s77, s75, 0
	s_add_u32 s38, s62, 0x80
	s_addc_u32 s39, s63, 0
	s_barrier
	v_add_u32_e32 v128, 0x18000, v208
	ds_read_b128 v[146:149], v128
	ds_read_b128 v[150:153], v128 offset:1024
	ds_read_b128 v[154:157], v128 offset:2048
	ds_read_b128 v[158:161], v128 offset:3072
	v_add_u32_e32 v128, 0x1c000, v208
	ds_read_b128 v[130:133], v128
	ds_read_b128 v[134:137], v128 offset:1024
	ds_read_b128 v[138:141], v128 offset:2048
	ds_read_b128 v[142:145], v128 offset:3072
	s_add_u32 s74, s74, 0x40000
	s_addc_u32 s75, s75, 0
	s_mov_b32 vcc_lo, m0
	s_mov_b32 m0, s92
	s_nop 0
	global_load_lds_dwordx4 v195, s[74:75]
	s_mov_b32 m0, vcc_lo
	s_nop 0
	s_mov_b32 vcc_lo, m0
	s_mov_b32 m0, s93
	s_nop 0
	global_load_lds_dwordx4 v197, s[74:75]
	s_mov_b32 m0, vcc_lo
	s_waitcnt lgkmcnt(0)
	ds_read_b128 v[162:165], v209 offset:32768
	ds_read_b128 v[166:169], v209 offset:33792
	ds_read_b128 v[170:173], v209 offset:34816
	ds_read_b128 v[174:177], v209 offset:35840
	ds_read_b128 v[178:181], v209 offset:36864
	ds_read_b128 v[182:185], v209 offset:37888
	ds_read_b128 v[186:189], v209 offset:38912
	ds_read_b128 v[190:193], v209 offset:39936
	s_waitcnt vmcnt(8)
	s_waitcnt lgkmcnt(0)
	s_setprio 1
	s_barrier
	v_mfma_f32_16x16x32_bf16 v[124:127], v[146:149], v[162:165], v[124:127]
	v_mfma_f32_16x16x32_bf16 v[120:123], v[154:157], v[162:165], v[120:123]
	v_mfma_f32_16x16x32_bf16 v[108:111], v[146:149], v[170:173], v[108:111]
	v_mfma_f32_16x16x32_bf16 v[104:107], v[154:157], v[170:173], v[104:107]
	v_mfma_f32_16x16x32_bf16 v[92:95], v[146:149], v[178:181], v[92:95]
	v_mfma_f32_16x16x32_bf16 v[88:91], v[154:157], v[178:181], v[88:91]
	v_mfma_f32_16x16x32_bf16 v[76:79], v[146:149], v[186:189], v[76:79]
	v_mfma_f32_16x16x32_bf16 v[72:75], v[154:157], v[186:189], v[72:75]
	v_mfma_f32_16x16x32_bf16 v[124:127], v[150:153], v[166:169], v[124:127]
	v_mfma_f32_16x16x32_bf16 v[120:123], v[158:161], v[166:169], v[120:123]
	v_mfma_f32_16x16x32_bf16 v[108:111], v[150:153], v[174:177], v[108:111]
	v_mfma_f32_16x16x32_bf16 v[104:107], v[158:161], v[174:177], v[104:107]
	v_mfma_f32_16x16x32_bf16 v[92:95], v[150:153], v[182:185], v[92:95]
	v_mfma_f32_16x16x32_bf16 v[88:91], v[158:161], v[182:185], v[88:91]
	v_mfma_f32_16x16x32_bf16 v[76:79], v[150:153], v[190:193], v[76:79]
	v_mfma_f32_16x16x32_bf16 v[72:75], v[158:161], v[190:193], v[72:75]
	s_setprio 0
	s_setprio 1
	v_mfma_f32_16x16x32_bf16 v[116:119], v[130:133], v[162:165], v[116:119]
	v_mfma_f32_16x16x32_bf16 v[112:115], v[138:141], v[162:165], v[112:115]
	v_mfma_f32_16x16x32_bf16 v[100:103], v[130:133], v[170:173], v[100:103]
	v_mfma_f32_16x16x32_bf16 v[96:99], v[138:141], v[170:173], v[96:99]
	v_mfma_f32_16x16x32_bf16 v[84:87], v[130:133], v[178:181], v[84:87]
	v_mfma_f32_16x16x32_bf16 v[80:83], v[138:141], v[178:181], v[80:83]
	v_mfma_f32_16x16x32_bf16 v[68:71], v[130:133], v[186:189], v[68:71]
	v_mfma_f32_16x16x32_bf16 v[64:67], v[138:141], v[186:189], v[64:67]
	v_mfma_f32_16x16x32_bf16 v[116:119], v[134:137], v[166:169], v[116:119]
	v_mfma_f32_16x16x32_bf16 v[112:115], v[142:145], v[166:169], v[112:115]
	v_mfma_f32_16x16x32_bf16 v[100:103], v[134:137], v[174:177], v[100:103]
	v_mfma_f32_16x16x32_bf16 v[96:99], v[142:145], v[174:177], v[96:99]
	v_mfma_f32_16x16x32_bf16 v[84:87], v[134:137], v[182:185], v[84:87]
	v_mfma_f32_16x16x32_bf16 v[80:83], v[142:145], v[182:185], v[80:83]
	v_mfma_f32_16x16x32_bf16 v[68:71], v[134:137], v[190:193], v[68:71]
	v_mfma_f32_16x16x32_bf16 v[64:67], v[142:145], v[190:193], v[64:67]
	s_setprio 0
	s_barrier
	s_mov_b32 s74, m0
	s_mov_b32 m0, s95
	s_nop 0
	global_load_lds_dwordx4 v196, s[38:39]
	s_mov_b32 m0, s74
	s_nop 0
	s_mov_b32 s74, m0
	s_mov_b32 m0, s96
	s_nop 0
	global_load_lds_dwordx4 v198, s[38:39]
	s_mov_b32 m0, s74
	s_add_u32 s38, s62, 0x40080
	s_addc_u32 s39, s63, 0
	s_mov_b32 s62, m0
	s_mov_b32 m0, s65
	s_nop 0
	global_load_lds_dwordx4 v196, s[38:39]
	s_mov_b32 m0, s62
	s_and_b64 vcc, exec, s[44:45]
	s_mov_b32 s62, m0
	s_mov_b32 m0, s50
	s_nop 0
	global_load_lds_dwordx4 v198, s[38:39]
	s_mov_b32 m0, s62
	s_mov_b32 s38, m0
	s_mov_b32 m0, s97
	s_nop 0
	global_load_lds_dwordx4 v195, s[76:77]
	s_mov_b32 m0, s38
	s_nop 0
	s_mov_b32 s38, m0
	s_mov_b32 m0, s9
	s_nop 0
	global_load_lds_dwordx4 v197, s[76:77]
	s_mov_b32 m0, s38
	ds_read_b128 v[186:189], v209 offset:49152
	ds_read_b128 v[190:193], v209 offset:50176
	ds_read_b128 v[178:181], v209 offset:51200
	ds_read_b128 v[182:185], v209 offset:52224
	ds_read_b128 v[170:173], v209 offset:53248
	ds_read_b128 v[174:177], v209 offset:54272
	ds_read_b128 v[162:165], v209 offset:55296
	ds_read_b128 v[166:169], v209 offset:56320
	s_waitcnt vmcnt(8)
	s_waitcnt lgkmcnt(0)
	s_barrier
	s_cbranch_vccnz .LBB0_412
	s_setprio 1
	v_mfma_f32_16x16x32_bf16 v[60:63], v[146:149], v[186:189], v[60:63]
	v_mfma_f32_16x16x32_bf16 v[56:59], v[154:157], v[186:189], v[56:59]
	v_mfma_f32_16x16x32_bf16 v[44:47], v[146:149], v[178:181], v[44:47]
	v_mfma_f32_16x16x32_bf16 v[40:43], v[154:157], v[178:181], v[40:43]
	v_mfma_f32_16x16x32_bf16 v[28:31], v[146:149], v[170:173], v[28:31]
	v_mfma_f32_16x16x32_bf16 v[24:27], v[154:157], v[170:173], v[24:27]
	v_mfma_f32_16x16x32_bf16 v[12:15], v[146:149], v[162:165], v[12:15]
	v_mfma_f32_16x16x32_bf16 v[8:11], v[154:157], v[162:165], v[8:11]
	v_mfma_f32_16x16x32_bf16 v[60:63], v[150:153], v[190:193], v[60:63]
	v_mfma_f32_16x16x32_bf16 v[56:59], v[158:161], v[190:193], v[56:59]
	v_mfma_f32_16x16x32_bf16 v[44:47], v[150:153], v[182:185], v[44:47]
	v_mfma_f32_16x16x32_bf16 v[40:43], v[158:161], v[182:185], v[40:43]
	v_mfma_f32_16x16x32_bf16 v[28:31], v[150:153], v[174:177], v[28:31]
	v_mfma_f32_16x16x32_bf16 v[24:27], v[158:161], v[174:177], v[24:27]
	v_mfma_f32_16x16x32_bf16 v[12:15], v[150:153], v[166:169], v[12:15]
	v_mfma_f32_16x16x32_bf16 v[8:11], v[158:161], v[166:169], v[8:11]
	s_setprio 0
	s_setprio 1
	v_mfma_f32_16x16x32_bf16 v[52:55], v[130:133], v[186:189], v[52:55]
	v_mfma_f32_16x16x32_bf16 v[48:51], v[138:141], v[186:189], v[48:51]
	v_mfma_f32_16x16x32_bf16 v[36:39], v[130:133], v[178:181], v[36:39]
	v_mfma_f32_16x16x32_bf16 v[32:35], v[138:141], v[178:181], v[32:35]
	v_mfma_f32_16x16x32_bf16 v[20:23], v[130:133], v[170:173], v[20:23]
	v_mfma_f32_16x16x32_bf16 v[16:19], v[138:141], v[170:173], v[16:19]
	v_mfma_f32_16x16x32_bf16 v[4:7], v[130:133], v[162:165], v[4:7]
	v_mfma_f32_16x16x32_bf16 v[0:3], v[138:141], v[162:165], v[0:3]
	v_mfma_f32_16x16x32_bf16 v[52:55], v[134:137], v[190:193], v[52:55]
	v_mfma_f32_16x16x32_bf16 v[48:51], v[142:145], v[190:193], v[48:51]
	v_mfma_f32_16x16x32_bf16 v[36:39], v[134:137], v[182:185], v[36:39]
	v_mfma_f32_16x16x32_bf16 v[32:35], v[142:145], v[182:185], v[32:35]
	v_mfma_f32_16x16x32_bf16 v[20:23], v[134:137], v[174:177], v[20:23]
	v_mfma_f32_16x16x32_bf16 v[16:19], v[142:145], v[174:177], v[16:19]
	v_mfma_f32_16x16x32_bf16 v[4:7], v[134:137], v[166:169], v[4:7]
	v_mfma_f32_16x16x32_bf16 v[0:3], v[142:145], v[166:169], v[0:3]
	s_setprio 0
	s_branch .LBB0_412
